# P5 residual epilogue: 32 residual loads batched in a 3-block register ring with counted vmcnt instead of one vmcnt(0) round trip per load
# speedup vs baseline: 1.0092x; 1.0071x over previous
; __device__ __forceinline__ unsigned cvt_pk_bf16(float lo, float hi) { unsigned r; asm volatile("v_cvt_pk_bf16_f32 %0, %1, %2" : "=v"(r) : "v"(lo), "v"(hi)); return r; }
;     __device__ __forceinline__ void operator()(const f32x4 (&acc)[2][2][4][2], const Unit& u, int wr, int wc, int fr, int fq) const {
;         const int row0 = u.pm * BM + wr * 64 + fr, col0 = u.pn * BM + wc * 32 + 4 * fq;
; #pragma unroll
;         for (int ai = 0; ai < 2; ++ai)
; #pragma unroll
;             for (int m = 0; m < 4; ++m) { const int row = row0 + ai * HALF + m * 16; const size_t ro = (size_t)row * 2048 + col0; float ss = 0.f;
; #pragma unroll
;                 for (int bj = 0; bj < 2; ++bj)
; #pragma unroll
;                     for (int n = 0; n < 2; ++n) { const size_t off = ro + bj * HALF + n * 16; const f32x4 hv = *(const f32x4*)(R + off) + acc[ai][bj][m][n];
;                         *(f32x4*)(H + off) = hv; ss += (hv[0] * hv[0] + hv[1] * hv[1]) + (hv[2] * hv[2] + hv[3] * hv[3]);
;                         if (WITH_A5) { const f32x4 gv = *(const f32x4*)(gm + col0 + bj * HALF + n * 16); u32x2 w; w.x = cvt_pk_bf16(hv[0] * gv[0], hv[1] * gv[1]); w.y = cvt_pk_bf16(hv[2] * gv[2], hv[3] * gv[3]); *(u32x2*)(a5 + off) = w; } }
;                 ss += __shfl_xor(ss, 16); ss += __shfl_xor(ss, 32);
;                 if (fq == 0) atomicAdd(rowss + row, ss); }
.LBB0_736:
	v_lshlrev_b32_e32 v222, 13, v146
	v_lshl_add_u32 v222, v148, 2, v222
	v_lshlrev_b32_e32 v153, 2, v146
	v_lshrrev_b32_e32 v223, 1, v222
	v_lshlrev_b32_e32 v154, 2, v148
	v_xor_b32_e32 v144, 16, v152
	v_xor_b32_e32 v145, 32, v152
	v_lshlrev_b32_e32 v144, 2, v144
	v_lshlrev_b32_e32 v145, 2, v145
	v_readlane_b32 s52, v234, 5
	v_readlane_b32 s53, v234, 6
	v_readlane_b32 s60, v234, 31
	v_readlane_b32 s61, v234, 32
	s_lshl_b32 s62, s2, 21
	s_lshl_b32 s63, s26, 10
	s_add_u32 s62, s62, s63
	s_nop 1
	s_add_u32 s52, s52, s62
	s_addc_u32 s53, s53, 0
	s_add_u32 s54, s86, s62
	s_addc_u32 s55, s87, 0
	s_add_u32 s60, s60, s63
	s_addc_u32 s61, s61, 0
	s_lshr_b32 s63, s62, 1
	s_add_u32 s56, s10, s63
	s_addc_u32 s57, s11, 0
	s_lshl_b32 s63, s2, 10
	s_add_u32 s58, s12, s63
	s_addc_u32 s59, s13, 0
	global_load_dwordx4 v[158:161], v154, s[60:61]
	global_load_dwordx4 v[162:165], v154, s[60:61] offset:64
	global_load_dwordx4 v[166:169], v154, s[60:61] offset:512
	global_load_dwordx4 v[170:173], v154, s[60:61] offset:576
	global_load_dwordx4 v[174:177], v222, s[52:53]
	global_load_dwordx4 v[178:181], v222, s[52:53] offset:64
	global_load_dwordx4 v[182:185], v222, s[52:53] offset:512
	global_load_dwordx4 v[186:189], v222, s[52:53] offset:576
	s_add_u32 s52, s52, 0x20000
	s_addc_u32 s53, s53, 0
	global_load_dwordx4 v[190:193], v222, s[52:53]
	global_load_dwordx4 v[194:197], v222, s[52:53] offset:64
	global_load_dwordx4 v[198:201], v222, s[52:53] offset:512
	global_load_dwordx4 v[202:205], v222, s[52:53] offset:576
	s_add_u32 s52, s52, 0x20000
	s_addc_u32 s53, s53, 0
	global_load_dwordx4 v[206:209], v222, s[52:53]
	global_load_dwordx4 v[210:213], v222, s[52:53] offset:64
	global_load_dwordx4 v[214:217], v222, s[52:53] offset:512
	global_load_dwordx4 v[218:221], v222, s[52:53] offset:576
	s_add_u32 s52, s52, 0x20000
	s_addc_u32 s53, s53, 0
	s_waitcnt vmcnt(8)
	v_pk_add_f32 v[124:125], v[124:125], v[174:175]
	v_pk_add_f32 v[126:127], v[126:127], v[176:177]
	v_pk_add_f32 v[120:121], v[120:121], v[178:179]
	v_pk_add_f32 v[122:123], v[122:123], v[180:181]
	v_pk_add_f32 v[116:117], v[116:117], v[182:183]
	v_pk_add_f32 v[118:119], v[118:119], v[184:185]
	v_pk_add_f32 v[112:113], v[112:113], v[186:187]
	v_pk_add_f32 v[114:115], v[114:115], v[188:189]
	global_load_dwordx4 v[174:177], v222, s[52:53]
	global_load_dwordx4 v[178:181], v222, s[52:53] offset:64
	global_load_dwordx4 v[182:185], v222, s[52:53] offset:512
	global_load_dwordx4 v[186:189], v222, s[52:53] offset:576
	s_add_u32 s52, s52, 0xa0000
	s_addc_u32 s53, s53, 0
	global_store_dwordx4 v222, v[124:127], s[54:55]
	global_store_dwordx4 v222, v[120:123], s[54:55] offset:64
	global_store_dwordx4 v222, v[116:119], s[54:55] offset:512
	global_store_dwordx4 v222, v[112:115], s[54:55] offset:576
	s_add_u32 s54, s54, 0x20000
	s_addc_u32 s55, s55, 0
	v_mul_f32_e32 v140, v124, v158
	v_mul_f32_e32 v141, v125, v159
	v_mul_f32_e32 v142, v126, v160
	v_mul_f32_e32 v143, v127, v161
	v_cvt_pk_bf16_f32 v224, v140, v141
	v_cvt_pk_bf16_f32 v225, v142, v143
	global_store_dwordx2 v223, v[224:225], s[56:57]
	v_mul_f32_e32 v140, v120, v162
	v_mul_f32_e32 v141, v121, v163
	v_mul_f32_e32 v142, v122, v164
	v_mul_f32_e32 v143, v123, v165
	v_cvt_pk_bf16_f32 v226, v140, v141
	v_cvt_pk_bf16_f32 v227, v142, v143
	global_store_dwordx2 v223, v[226:227], s[56:57] offset:32
	v_mul_f32_e32 v140, v116, v166
	v_mul_f32_e32 v141, v117, v167
	v_mul_f32_e32 v142, v118, v168
	v_mul_f32_e32 v143, v119, v169
	v_cvt_pk_bf16_f32 v228, v140, v141
	v_cvt_pk_bf16_f32 v229, v142, v143
	global_store_dwordx2 v223, v[228:229], s[56:57] offset:256
	v_mul_f32_e32 v140, v112, v170
	v_mul_f32_e32 v141, v113, v171
	v_mul_f32_e32 v142, v114, v172
	v_mul_f32_e32 v143, v115, v173
	v_cvt_pk_bf16_f32 v230, v140, v141
	v_cvt_pk_bf16_f32 v231, v142, v143
	global_store_dwordx2 v223, v[230:231], s[56:57] offset:288
	s_add_u32 s56, s56, 0x10000
	s_addc_u32 s57, s57, 0
	v_mul_f32_e32 v140, v125, v125
	v_mul_f32_e32 v141, v127, v127
	v_fmac_f32_e32 v140, v124, v124
	v_fmac_f32_e32 v141, v126, v126
	v_add_f32_e32 v142, v140, v141
	v_mul_f32_e32 v140, v121, v121
	v_mul_f32_e32 v141, v123, v123
	v_fmac_f32_e32 v140, v120, v120
	v_fmac_f32_e32 v141, v122, v122
	v_add_f32_e32 v140, v140, v141
	v_add_f32_e32 v142, v142, v140
	v_mul_f32_e32 v140, v117, v117
	v_mul_f32_e32 v141, v119, v119
	v_fmac_f32_e32 v140, v116, v116
	v_fmac_f32_e32 v141, v118, v118
	v_add_f32_e32 v140, v140, v141
	v_add_f32_e32 v142, v142, v140
	v_mul_f32_e32 v140, v113, v113
	v_mul_f32_e32 v141, v115, v115
	v_fmac_f32_e32 v140, v112, v112
	v_fmac_f32_e32 v141, v114, v114
	v_add_f32_e32 v140, v140, v141
	v_add_f32_e32 v142, v142, v140
	v_mov_b32_e32 v112, v142
	s_waitcnt vmcnt(16)
; __device__ __forceinline__ unsigned cvt_pk_bf16(float lo, float hi) { unsigned r; asm volatile("v_cvt_pk_bf16_f32 %0, %1, %2" : "=v"(r) : "v"(lo), "v"(hi)); return r; }
;     __device__ __forceinline__ void operator()(const f32x4 (&acc)[2][2][4][2], const Unit& u, int wr, int wc, int fr, int fq) const {
;     ...
;             for (int m = 0; m < 4; ++m) { const int row = row0 + ai * HALF + m * 16; const size_t ro = (size_t)row * 2048 + col0; float ss = 0.f;
; #pragma unroll
;                 for (int bj = 0; bj < 2; ++bj)
; #pragma unroll
;                     for (int n = 0; n < 2; ++n) { const size_t off = ro + bj * HALF + n * 16; const f32x4 hv = *(const f32x4*)(R + off) + acc[ai][bj][m][n];
;                         *(f32x4*)(H + off) = hv; ss += (hv[0] * hv[0] + hv[1] * hv[1]) + (hv[2] * hv[2] + hv[3] * hv[3]);
;                         if (WITH_A5) { const f32x4 gv = *(const f32x4*)(gm + col0 + bj * HALF + n * 16); u32x2 w; w.x = cvt_pk_bf16(hv[0] * gv[0], hv[1] * gv[1]); w.y = cvt_pk_bf16(hv[2] * gv[2], hv[3] * gv[3]); *(u32x2*)(a5 + off) = w; } }
	v_pk_add_f32 v[108:109], v[108:109], v[190:191]
	v_pk_add_f32 v[110:111], v[110:111], v[192:193]
	v_pk_add_f32 v[104:105], v[104:105], v[194:195]
	v_pk_add_f32 v[106:107], v[106:107], v[196:197]
	v_pk_add_f32 v[100:101], v[100:101], v[198:199]
	v_pk_add_f32 v[102:103], v[102:103], v[200:201]
	v_pk_add_f32 v[96:97], v[96:97], v[202:203]
	v_pk_add_f32 v[98:99], v[98:99], v[204:205]
	global_load_dwordx4 v[190:193], v222, s[52:53]
	global_load_dwordx4 v[194:197], v222, s[52:53] offset:64
	global_load_dwordx4 v[198:201], v222, s[52:53] offset:512
	global_load_dwordx4 v[202:205], v222, s[52:53] offset:576
	s_add_u32 s52, s52, 0x20000
	s_addc_u32 s53, s53, 0
	global_store_dwordx4 v222, v[108:111], s[54:55]
	global_store_dwordx4 v222, v[104:107], s[54:55] offset:64
	global_store_dwordx4 v222, v[100:103], s[54:55] offset:512
	global_store_dwordx4 v222, v[96:99], s[54:55] offset:576
	s_add_u32 s54, s54, 0x20000
	s_addc_u32 s55, s55, 0
	v_mul_f32_e32 v140, v108, v158
	v_mul_f32_e32 v141, v109, v159
	v_mul_f32_e32 v142, v110, v160
	v_mul_f32_e32 v143, v111, v161
	v_cvt_pk_bf16_f32 v224, v140, v141
	v_cvt_pk_bf16_f32 v225, v142, v143
	global_store_dwordx2 v223, v[224:225], s[56:57]
	v_mul_f32_e32 v140, v104, v162
	v_mul_f32_e32 v141, v105, v163
	v_mul_f32_e32 v142, v106, v164
	v_mul_f32_e32 v143, v107, v165
	v_cvt_pk_bf16_f32 v226, v140, v141
	v_cvt_pk_bf16_f32 v227, v142, v143
	global_store_dwordx2 v223, v[226:227], s[56:57] offset:32
	v_mul_f32_e32 v140, v100, v166
	v_mul_f32_e32 v141, v101, v167
	v_mul_f32_e32 v142, v102, v168
	v_mul_f32_e32 v143, v103, v169
	v_cvt_pk_bf16_f32 v228, v140, v141
	v_cvt_pk_bf16_f32 v229, v142, v143
	global_store_dwordx2 v223, v[228:229], s[56:57] offset:256
	v_mul_f32_e32 v140, v96, v170
	v_mul_f32_e32 v141, v97, v171
	v_mul_f32_e32 v142, v98, v172
	v_mul_f32_e32 v143, v99, v173
	v_cvt_pk_bf16_f32 v230, v140, v141
	v_cvt_pk_bf16_f32 v231, v142, v143
	global_store_dwordx2 v223, v[230:231], s[56:57] offset:288
	s_add_u32 s56, s56, 0x10000
	s_addc_u32 s57, s57, 0
	v_mul_f32_e32 v140, v109, v109
	v_mul_f32_e32 v141, v111, v111
	v_fmac_f32_e32 v140, v108, v108
	v_fmac_f32_e32 v141, v110, v110
	v_add_f32_e32 v142, v140, v141
	v_mul_f32_e32 v140, v105, v105
	v_mul_f32_e32 v141, v107, v107
	v_fmac_f32_e32 v140, v104, v104
	v_fmac_f32_e32 v141, v106, v106
	v_add_f32_e32 v140, v140, v141
	v_add_f32_e32 v142, v142, v140
	v_mul_f32_e32 v140, v101, v101
	v_mul_f32_e32 v141, v103, v103
	v_fmac_f32_e32 v140, v100, v100
	v_fmac_f32_e32 v141, v102, v102
	v_add_f32_e32 v140, v140, v141
	v_add_f32_e32 v142, v142, v140
	v_mul_f32_e32 v140, v97, v97
	v_mul_f32_e32 v141, v99, v99
	v_fmac_f32_e32 v140, v96, v96
	v_fmac_f32_e32 v141, v98, v98
	v_add_f32_e32 v140, v140, v141
	v_add_f32_e32 v142, v142, v140
	v_mov_b32_e32 v96, v142
	s_waitcnt vmcnt(24)
	v_pk_add_f32 v[92:93], v[92:93], v[206:207]
	v_pk_add_f32 v[94:95], v[94:95], v[208:209]
	v_pk_add_f32 v[88:89], v[88:89], v[210:211]
	v_pk_add_f32 v[90:91], v[90:91], v[212:213]
	v_pk_add_f32 v[84:85], v[84:85], v[214:215]
	v_pk_add_f32 v[86:87], v[86:87], v[216:217]
	v_pk_add_f32 v[80:81], v[80:81], v[218:219]
	v_pk_add_f32 v[82:83], v[82:83], v[220:221]
	global_load_dwordx4 v[206:209], v222, s[52:53]
	global_load_dwordx4 v[210:213], v222, s[52:53] offset:64
	global_load_dwordx4 v[214:217], v222, s[52:53] offset:512
	global_load_dwordx4 v[218:221], v222, s[52:53] offset:576
	s_add_u32 s52, s52, 0x20000
	s_addc_u32 s53, s53, 0
	global_store_dwordx4 v222, v[92:95], s[54:55]
	global_store_dwordx4 v222, v[88:91], s[54:55] offset:64
	global_store_dwordx4 v222, v[84:87], s[54:55] offset:512
	global_store_dwordx4 v222, v[80:83], s[54:55] offset:576
	s_add_u32 s54, s54, 0x20000
	s_addc_u32 s55, s55, 0
	v_mul_f32_e32 v140, v92, v158
	v_mul_f32_e32 v141, v93, v159
	v_mul_f32_e32 v142, v94, v160
	v_mul_f32_e32 v143, v95, v161
	v_cvt_pk_bf16_f32 v224, v140, v141
	v_cvt_pk_bf16_f32 v225, v142, v143
	global_store_dwordx2 v223, v[224:225], s[56:57]
	v_mul_f32_e32 v140, v88, v162
	v_mul_f32_e32 v141, v89, v163
	v_mul_f32_e32 v142, v90, v164
	v_mul_f32_e32 v143, v91, v165
	v_cvt_pk_bf16_f32 v226, v140, v141
	v_cvt_pk_bf16_f32 v227, v142, v143
	global_store_dwordx2 v223, v[226:227], s[56:57] offset:32
	v_mul_f32_e32 v140, v84, v166
	v_mul_f32_e32 v141, v85, v167
	v_mul_f32_e32 v142, v86, v168
	v_mul_f32_e32 v143, v87, v169
	v_cvt_pk_bf16_f32 v228, v140, v141
	v_cvt_pk_bf16_f32 v229, v142, v143
	global_store_dwordx2 v223, v[228:229], s[56:57] offset:256
	v_mul_f32_e32 v140, v80, v170
	v_mul_f32_e32 v141, v81, v171
	v_mul_f32_e32 v142, v82, v172
	v_mul_f32_e32 v143, v83, v173
	v_cvt_pk_bf16_f32 v230, v140, v141
	v_cvt_pk_bf16_f32 v231, v142, v143
	global_store_dwordx2 v223, v[230:231], s[56:57] offset:288
	s_add_u32 s56, s56, 0x10000
	s_addc_u32 s57, s57, 0
	v_mul_f32_e32 v140, v93, v93
	v_mul_f32_e32 v141, v95, v95
	v_fmac_f32_e32 v140, v92, v92
	v_fmac_f32_e32 v141, v94, v94
	v_add_f32_e32 v142, v140, v141
	v_mul_f32_e32 v140, v89, v89
	v_mul_f32_e32 v141, v91, v91
	v_fmac_f32_e32 v140, v88, v88
	v_fmac_f32_e32 v141, v90, v90
	v_add_f32_e32 v140, v140, v141
	v_add_f32_e32 v142, v142, v140
	v_mul_f32_e32 v140, v85, v85
	v_mul_f32_e32 v141, v87, v87
	v_fmac_f32_e32 v140, v84, v84
	v_fmac_f32_e32 v141, v86, v86
	v_add_f32_e32 v140, v140, v141
	v_add_f32_e32 v142, v142, v140
	v_mul_f32_e32 v140, v81, v81
	v_mul_f32_e32 v141, v83, v83
	v_fmac_f32_e32 v140, v80, v80
	v_fmac_f32_e32 v141, v82, v82
	v_add_f32_e32 v140, v140, v141
	v_add_f32_e32 v142, v142, v140
	v_mov_b32_e32 v80, v142
	s_waitcnt vmcnt(32)
; __device__ __forceinline__ unsigned cvt_pk_bf16(float lo, float hi) { unsigned r; asm volatile("v_cvt_pk_bf16_f32 %0, %1, %2" : "=v"(r) : "v"(lo), "v"(hi)); return r; }
;     __device__ __forceinline__ void operator()(const f32x4 (&acc)[2][2][4][2], const Unit& u, int wr, int wc, int fr, int fq) const {
;     ...
;             for (int m = 0; m < 4; ++m) { const int row = row0 + ai * HALF + m * 16; const size_t ro = (size_t)row * 2048 + col0; float ss = 0.f;
; #pragma unroll
;                 for (int bj = 0; bj < 2; ++bj)
; #pragma unroll
;                     for (int n = 0; n < 2; ++n) { const size_t off = ro + bj * HALF + n * 16; const f32x4 hv = *(const f32x4*)(R + off) + acc[ai][bj][m][n];
;                         *(f32x4*)(H + off) = hv; ss += (hv[0] * hv[0] + hv[1] * hv[1]) + (hv[2] * hv[2] + hv[3] * hv[3]);
;                         if (WITH_A5) { const f32x4 gv = *(const f32x4*)(gm + col0 + bj * HALF + n * 16); u32x2 w; w.x = cvt_pk_bf16(hv[0] * gv[0], hv[1] * gv[1]); w.y = cvt_pk_bf16(hv[2] * gv[2], hv[3] * gv[3]); *(u32x2*)(a5 + off) = w; } }
	v_pk_add_f32 v[76:77], v[76:77], v[174:175]
	v_pk_add_f32 v[78:79], v[78:79], v[176:177]
	v_pk_add_f32 v[72:73], v[72:73], v[178:179]
	v_pk_add_f32 v[74:75], v[74:75], v[180:181]
	v_pk_add_f32 v[68:69], v[68:69], v[182:183]
	v_pk_add_f32 v[70:71], v[70:71], v[184:185]
	v_pk_add_f32 v[64:65], v[64:65], v[186:187]
	v_pk_add_f32 v[66:67], v[66:67], v[188:189]
	global_load_dwordx4 v[174:177], v222, s[52:53]
	global_load_dwordx4 v[178:181], v222, s[52:53] offset:64
	global_load_dwordx4 v[182:185], v222, s[52:53] offset:512
	global_load_dwordx4 v[186:189], v222, s[52:53] offset:576
	s_add_u32 s52, s52, 0x20000
	s_addc_u32 s53, s53, 0
	global_store_dwordx4 v222, v[76:79], s[54:55]
	global_store_dwordx4 v222, v[72:75], s[54:55] offset:64
	global_store_dwordx4 v222, v[68:71], s[54:55] offset:512
	global_store_dwordx4 v222, v[64:67], s[54:55] offset:576
	s_add_u32 s54, s54, 0xa0000
	s_addc_u32 s55, s55, 0
	v_mul_f32_e32 v140, v76, v158
	v_mul_f32_e32 v141, v77, v159
	v_mul_f32_e32 v142, v78, v160
	v_mul_f32_e32 v143, v79, v161
	v_cvt_pk_bf16_f32 v224, v140, v141
	v_cvt_pk_bf16_f32 v225, v142, v143
	global_store_dwordx2 v223, v[224:225], s[56:57]
	v_mul_f32_e32 v140, v72, v162
	v_mul_f32_e32 v141, v73, v163
	v_mul_f32_e32 v142, v74, v164
	v_mul_f32_e32 v143, v75, v165
	v_cvt_pk_bf16_f32 v226, v140, v141
	v_cvt_pk_bf16_f32 v227, v142, v143
	global_store_dwordx2 v223, v[226:227], s[56:57] offset:32
	v_mul_f32_e32 v140, v68, v166
	v_mul_f32_e32 v141, v69, v167
	v_mul_f32_e32 v142, v70, v168
	v_mul_f32_e32 v143, v71, v169
	v_cvt_pk_bf16_f32 v228, v140, v141
	v_cvt_pk_bf16_f32 v229, v142, v143
	global_store_dwordx2 v223, v[228:229], s[56:57] offset:256
	v_mul_f32_e32 v140, v64, v170
	v_mul_f32_e32 v141, v65, v171
	v_mul_f32_e32 v142, v66, v172
	v_mul_f32_e32 v143, v67, v173
	v_cvt_pk_bf16_f32 v230, v140, v141
	v_cvt_pk_bf16_f32 v231, v142, v143
	global_store_dwordx2 v223, v[230:231], s[56:57] offset:288
	s_add_u32 s56, s56, 0x50000
	s_addc_u32 s57, s57, 0
	v_mul_f32_e32 v140, v77, v77
	v_mul_f32_e32 v141, v79, v79
	v_fmac_f32_e32 v140, v76, v76
	v_fmac_f32_e32 v141, v78, v78
	v_add_f32_e32 v142, v140, v141
	v_mul_f32_e32 v140, v73, v73
	v_mul_f32_e32 v141, v75, v75
	v_fmac_f32_e32 v140, v72, v72
	v_fmac_f32_e32 v141, v74, v74
	v_add_f32_e32 v140, v140, v141
	v_add_f32_e32 v142, v142, v140
	v_mul_f32_e32 v140, v69, v69
	v_mul_f32_e32 v141, v71, v71
	v_fmac_f32_e32 v140, v68, v68
	v_fmac_f32_e32 v141, v70, v70
	v_add_f32_e32 v140, v140, v141
	v_add_f32_e32 v142, v142, v140
	v_mul_f32_e32 v140, v65, v65
	v_mul_f32_e32 v141, v67, v67
	v_fmac_f32_e32 v140, v64, v64
	v_fmac_f32_e32 v141, v66, v66
	v_add_f32_e32 v140, v140, v141
	v_add_f32_e32 v142, v142, v140
	v_mov_b32_e32 v64, v142
	s_waitcnt vmcnt(32)
	v_pk_add_f32 v[60:61], v[60:61], v[190:191]
	v_pk_add_f32 v[62:63], v[62:63], v[192:193]
	v_pk_add_f32 v[56:57], v[56:57], v[194:195]
	v_pk_add_f32 v[58:59], v[58:59], v[196:197]
	v_pk_add_f32 v[52:53], v[52:53], v[198:199]
	v_pk_add_f32 v[54:55], v[54:55], v[200:201]
	v_pk_add_f32 v[48:49], v[48:49], v[202:203]
	v_pk_add_f32 v[50:51], v[50:51], v[204:205]
	global_load_dwordx4 v[190:193], v222, s[52:53]
	global_load_dwordx4 v[194:197], v222, s[52:53] offset:64
	global_load_dwordx4 v[198:201], v222, s[52:53] offset:512
	global_load_dwordx4 v[202:205], v222, s[52:53] offset:576
	global_store_dwordx4 v222, v[60:63], s[54:55]
	global_store_dwordx4 v222, v[56:59], s[54:55] offset:64
	global_store_dwordx4 v222, v[52:55], s[54:55] offset:512
	global_store_dwordx4 v222, v[48:51], s[54:55] offset:576
	s_add_u32 s54, s54, 0x20000
	s_addc_u32 s55, s55, 0
	v_mul_f32_e32 v140, v60, v158
	v_mul_f32_e32 v141, v61, v159
	v_mul_f32_e32 v142, v62, v160
	v_mul_f32_e32 v143, v63, v161
	v_cvt_pk_bf16_f32 v224, v140, v141
	v_cvt_pk_bf16_f32 v225, v142, v143
	global_store_dwordx2 v223, v[224:225], s[56:57]
	v_mul_f32_e32 v140, v56, v162
	v_mul_f32_e32 v141, v57, v163
	v_mul_f32_e32 v142, v58, v164
	v_mul_f32_e32 v143, v59, v165
	v_cvt_pk_bf16_f32 v226, v140, v141
	v_cvt_pk_bf16_f32 v227, v142, v143
	global_store_dwordx2 v223, v[226:227], s[56:57] offset:32
	v_mul_f32_e32 v140, v52, v166
	v_mul_f32_e32 v141, v53, v167
	v_mul_f32_e32 v142, v54, v168
	v_mul_f32_e32 v143, v55, v169
	v_cvt_pk_bf16_f32 v228, v140, v141
	v_cvt_pk_bf16_f32 v229, v142, v143
	global_store_dwordx2 v223, v[228:229], s[56:57] offset:256
	v_mul_f32_e32 v140, v48, v170
	v_mul_f32_e32 v141, v49, v171
	v_mul_f32_e32 v142, v50, v172
	v_mul_f32_e32 v143, v51, v173
	v_cvt_pk_bf16_f32 v230, v140, v141
	v_cvt_pk_bf16_f32 v231, v142, v143
	global_store_dwordx2 v223, v[230:231], s[56:57] offset:288
	s_add_u32 s56, s56, 0x10000
	s_addc_u32 s57, s57, 0
	v_mul_f32_e32 v140, v61, v61
	v_mul_f32_e32 v141, v63, v63
	v_fmac_f32_e32 v140, v60, v60
	v_fmac_f32_e32 v141, v62, v62
	v_add_f32_e32 v142, v140, v141
	v_mul_f32_e32 v140, v57, v57
	v_mul_f32_e32 v141, v59, v59
	v_fmac_f32_e32 v140, v56, v56
	v_fmac_f32_e32 v141, v58, v58
	v_add_f32_e32 v140, v140, v141
	v_add_f32_e32 v142, v142, v140
	v_mul_f32_e32 v140, v53, v53
	v_mul_f32_e32 v141, v55, v55
	v_fmac_f32_e32 v140, v52, v52
	v_fmac_f32_e32 v141, v54, v54
	v_add_f32_e32 v140, v140, v141
	v_add_f32_e32 v142, v142, v140
	v_mul_f32_e32 v140, v49, v49
	v_mul_f32_e32 v141, v51, v51
	v_fmac_f32_e32 v140, v48, v48
	v_fmac_f32_e32 v141, v50, v50
	v_add_f32_e32 v140, v140, v141
	v_add_f32_e32 v142, v142, v140
	v_mov_b32_e32 v48, v142
	s_waitcnt vmcnt(32)
; __device__ __forceinline__ unsigned cvt_pk_bf16(float lo, float hi) { unsigned r; asm volatile("v_cvt_pk_bf16_f32 %0, %1, %2" : "=v"(r) : "v"(lo), "v"(hi)); return r; }
;     __device__ __forceinline__ void operator()(const f32x4 (&acc)[2][2][4][2], const Unit& u, int wr, int wc, int fr, int fq) const {
;     ...
;             for (int m = 0; m < 4; ++m) { const int row = row0 + ai * HALF + m * 16; const size_t ro = (size_t)row * 2048 + col0; float ss = 0.f;
; #pragma unroll
;                 for (int bj = 0; bj < 2; ++bj)
; #pragma unroll
;                     for (int n = 0; n < 2; ++n) { const size_t off = ro + bj * HALF + n * 16; const f32x4 hv = *(const f32x4*)(R + off) + acc[ai][bj][m][n];
;                         *(f32x4*)(H + off) = hv; ss += (hv[0] * hv[0] + hv[1] * hv[1]) + (hv[2] * hv[2] + hv[3] * hv[3]);
;                         if (WITH_A5) { const f32x4 gv = *(const f32x4*)(gm + col0 + bj * HALF + n * 16); u32x2 w; w.x = cvt_pk_bf16(hv[0] * gv[0], hv[1] * gv[1]); w.y = cvt_pk_bf16(hv[2] * gv[2], hv[3] * gv[3]); *(u32x2*)(a5 + off) = w; } }
	v_pk_add_f32 v[44:45], v[44:45], v[206:207]
	v_pk_add_f32 v[46:47], v[46:47], v[208:209]
	v_pk_add_f32 v[40:41], v[40:41], v[210:211]
	v_pk_add_f32 v[42:43], v[42:43], v[212:213]
	v_pk_add_f32 v[36:37], v[36:37], v[214:215]
	v_pk_add_f32 v[38:39], v[38:39], v[216:217]
	v_pk_add_f32 v[32:33], v[32:33], v[218:219]
	v_pk_add_f32 v[34:35], v[34:35], v[220:221]
	global_store_dwordx4 v222, v[44:47], s[54:55]
	global_store_dwordx4 v222, v[40:43], s[54:55] offset:64
	global_store_dwordx4 v222, v[36:39], s[54:55] offset:512
	global_store_dwordx4 v222, v[32:35], s[54:55] offset:576
	s_add_u32 s54, s54, 0x20000
	s_addc_u32 s55, s55, 0
	v_mul_f32_e32 v140, v44, v158
	v_mul_f32_e32 v141, v45, v159
	v_mul_f32_e32 v142, v46, v160
	v_mul_f32_e32 v143, v47, v161
	v_cvt_pk_bf16_f32 v224, v140, v141
	v_cvt_pk_bf16_f32 v225, v142, v143
	global_store_dwordx2 v223, v[224:225], s[56:57]
	v_mul_f32_e32 v140, v40, v162
	v_mul_f32_e32 v141, v41, v163
	v_mul_f32_e32 v142, v42, v164
	v_mul_f32_e32 v143, v43, v165
	v_cvt_pk_bf16_f32 v226, v140, v141
	v_cvt_pk_bf16_f32 v227, v142, v143
	global_store_dwordx2 v223, v[226:227], s[56:57] offset:32
	v_mul_f32_e32 v140, v36, v166
	v_mul_f32_e32 v141, v37, v167
	v_mul_f32_e32 v142, v38, v168
	v_mul_f32_e32 v143, v39, v169
	v_cvt_pk_bf16_f32 v228, v140, v141
	v_cvt_pk_bf16_f32 v229, v142, v143
	global_store_dwordx2 v223, v[228:229], s[56:57] offset:256
	v_mul_f32_e32 v140, v32, v170
	v_mul_f32_e32 v141, v33, v171
	v_mul_f32_e32 v142, v34, v172
	v_mul_f32_e32 v143, v35, v173
	v_cvt_pk_bf16_f32 v230, v140, v141
	v_cvt_pk_bf16_f32 v231, v142, v143
	global_store_dwordx2 v223, v[230:231], s[56:57] offset:288
	s_add_u32 s56, s56, 0x10000
	s_addc_u32 s57, s57, 0
	v_mul_f32_e32 v140, v45, v45
	v_mul_f32_e32 v141, v47, v47
	v_fmac_f32_e32 v140, v44, v44
	v_fmac_f32_e32 v141, v46, v46
	v_add_f32_e32 v142, v140, v141
	v_mul_f32_e32 v140, v41, v41
	v_mul_f32_e32 v141, v43, v43
	v_fmac_f32_e32 v140, v40, v40
	v_fmac_f32_e32 v141, v42, v42
	v_add_f32_e32 v140, v140, v141
	v_add_f32_e32 v142, v142, v140
	v_mul_f32_e32 v140, v37, v37
	v_mul_f32_e32 v141, v39, v39
	v_fmac_f32_e32 v140, v36, v36
	v_fmac_f32_e32 v141, v38, v38
	v_add_f32_e32 v140, v140, v141
	v_add_f32_e32 v142, v142, v140
	v_mul_f32_e32 v140, v33, v33
	v_mul_f32_e32 v141, v35, v35
	v_fmac_f32_e32 v140, v32, v32
	v_fmac_f32_e32 v141, v34, v34
	v_add_f32_e32 v140, v140, v141
	v_add_f32_e32 v142, v142, v140
	v_mov_b32_e32 v32, v142
	s_waitcnt vmcnt(28)
	v_pk_add_f32 v[28:29], v[28:29], v[174:175]
	v_pk_add_f32 v[30:31], v[30:31], v[176:177]
	v_pk_add_f32 v[24:25], v[24:25], v[178:179]
	v_pk_add_f32 v[26:27], v[26:27], v[180:181]
	v_pk_add_f32 v[20:21], v[20:21], v[182:183]
	v_pk_add_f32 v[22:23], v[22:23], v[184:185]
	v_pk_add_f32 v[16:17], v[16:17], v[186:187]
	v_pk_add_f32 v[18:19], v[18:19], v[188:189]
	global_store_dwordx4 v222, v[28:31], s[54:55]
	global_store_dwordx4 v222, v[24:27], s[54:55] offset:64
	global_store_dwordx4 v222, v[20:23], s[54:55] offset:512
	global_store_dwordx4 v222, v[16:19], s[54:55] offset:576
	s_add_u32 s54, s54, 0x20000
	s_addc_u32 s55, s55, 0
	v_mul_f32_e32 v140, v28, v158
	v_mul_f32_e32 v141, v29, v159
	v_mul_f32_e32 v142, v30, v160
	v_mul_f32_e32 v143, v31, v161
	v_cvt_pk_bf16_f32 v224, v140, v141
	v_cvt_pk_bf16_f32 v225, v142, v143
	global_store_dwordx2 v223, v[224:225], s[56:57]
	v_mul_f32_e32 v140, v24, v162
	v_mul_f32_e32 v141, v25, v163
	v_mul_f32_e32 v142, v26, v164
	v_mul_f32_e32 v143, v27, v165
	v_cvt_pk_bf16_f32 v226, v140, v141
	v_cvt_pk_bf16_f32 v227, v142, v143
	global_store_dwordx2 v223, v[226:227], s[56:57] offset:32
	v_mul_f32_e32 v140, v20, v166
	v_mul_f32_e32 v141, v21, v167
	v_mul_f32_e32 v142, v22, v168
	v_mul_f32_e32 v143, v23, v169
	v_cvt_pk_bf16_f32 v228, v140, v141
	v_cvt_pk_bf16_f32 v229, v142, v143
	global_store_dwordx2 v223, v[228:229], s[56:57] offset:256
	v_mul_f32_e32 v140, v16, v170
	v_mul_f32_e32 v141, v17, v171
	v_mul_f32_e32 v142, v18, v172
	v_mul_f32_e32 v143, v19, v173
	v_cvt_pk_bf16_f32 v230, v140, v141
	v_cvt_pk_bf16_f32 v231, v142, v143
	global_store_dwordx2 v223, v[230:231], s[56:57] offset:288
	s_add_u32 s56, s56, 0x10000
	s_addc_u32 s57, s57, 0
	v_mul_f32_e32 v140, v29, v29
	v_mul_f32_e32 v141, v31, v31
	v_fmac_f32_e32 v140, v28, v28
	v_fmac_f32_e32 v141, v30, v30
	v_add_f32_e32 v142, v140, v141
	v_mul_f32_e32 v140, v25, v25
	v_mul_f32_e32 v141, v27, v27
	v_fmac_f32_e32 v140, v24, v24
	v_fmac_f32_e32 v141, v26, v26
	v_add_f32_e32 v140, v140, v141
	v_add_f32_e32 v142, v142, v140
	v_mul_f32_e32 v140, v21, v21
	v_mul_f32_e32 v141, v23, v23
	v_fmac_f32_e32 v140, v20, v20
	v_fmac_f32_e32 v141, v22, v22
	v_add_f32_e32 v140, v140, v141
	v_add_f32_e32 v142, v142, v140
	v_mul_f32_e32 v140, v17, v17
	v_mul_f32_e32 v141, v19, v19
	v_fmac_f32_e32 v140, v16, v16
	v_fmac_f32_e32 v141, v18, v18
	v_add_f32_e32 v140, v140, v141
	v_add_f32_e32 v142, v142, v140
	v_mov_b32_e32 v16, v142
	s_waitcnt vmcnt(24)
; __device__ __forceinline__ unsigned cvt_pk_bf16(float lo, float hi) { unsigned r; asm volatile("v_cvt_pk_bf16_f32 %0, %1, %2" : "=v"(r) : "v"(lo), "v"(hi)); return r; }
;     __device__ __forceinline__ void operator()(const f32x4 (&acc)[2][2][4][2], const Unit& u, int wr, int wc, int fr, int fq) const {
;     ...
;                     for (int n = 0; n < 2; ++n) { const size_t off = ro + bj * HALF + n * 16; const f32x4 hv = *(const f32x4*)(R + off) + acc[ai][bj][m][n];
;                         *(f32x4*)(H + off) = hv; ss += (hv[0] * hv[0] + hv[1] * hv[1]) + (hv[2] * hv[2] + hv[3] * hv[3]);
;                         if (WITH_A5) { const f32x4 gv = *(const f32x4*)(gm + col0 + bj * HALF + n * 16); u32x2 w; w.x = cvt_pk_bf16(hv[0] * gv[0], hv[1] * gv[1]); w.y = cvt_pk_bf16(hv[2] * gv[2], hv[3] * gv[3]); *(u32x2*)(a5 + off) = w; } }
;                 ss += __shfl_xor(ss, 16); ss += __shfl_xor(ss, 32);
;                 if (fq == 0) atomicAdd(rowss + row, ss); }
	v_pk_add_f32 v[12:13], v[12:13], v[190:191]
	v_pk_add_f32 v[14:15], v[14:15], v[192:193]
	v_pk_add_f32 v[8:9], v[8:9], v[194:195]
	v_pk_add_f32 v[10:11], v[10:11], v[196:197]
	v_pk_add_f32 v[4:5], v[4:5], v[198:199]
	v_pk_add_f32 v[6:7], v[6:7], v[200:201]
	v_pk_add_f32 v[0:1], v[0:1], v[202:203]
	v_pk_add_f32 v[2:3], v[2:3], v[204:205]
	global_store_dwordx4 v222, v[12:15], s[54:55]
	global_store_dwordx4 v222, v[8:11], s[54:55] offset:64
	global_store_dwordx4 v222, v[4:7], s[54:55] offset:512
	global_store_dwordx4 v222, v[0:3], s[54:55] offset:576
	v_mul_f32_e32 v140, v12, v158
	v_mul_f32_e32 v141, v13, v159
	v_mul_f32_e32 v142, v14, v160
	v_mul_f32_e32 v143, v15, v161
	v_cvt_pk_bf16_f32 v224, v140, v141
	v_cvt_pk_bf16_f32 v225, v142, v143
	global_store_dwordx2 v223, v[224:225], s[56:57]
	v_mul_f32_e32 v140, v8, v162
	v_mul_f32_e32 v141, v9, v163
	v_mul_f32_e32 v142, v10, v164
	v_mul_f32_e32 v143, v11, v165
	v_cvt_pk_bf16_f32 v226, v140, v141
	v_cvt_pk_bf16_f32 v227, v142, v143
	global_store_dwordx2 v223, v[226:227], s[56:57] offset:32
	v_mul_f32_e32 v140, v4, v166
	v_mul_f32_e32 v141, v5, v167
	v_mul_f32_e32 v142, v6, v168
	v_mul_f32_e32 v143, v7, v169
	v_cvt_pk_bf16_f32 v228, v140, v141
	v_cvt_pk_bf16_f32 v229, v142, v143
	global_store_dwordx2 v223, v[228:229], s[56:57] offset:256
	v_mul_f32_e32 v140, v0, v170
	v_mul_f32_e32 v141, v1, v171
	v_mul_f32_e32 v142, v2, v172
	v_mul_f32_e32 v143, v3, v173
	v_cvt_pk_bf16_f32 v230, v140, v141
	v_cvt_pk_bf16_f32 v231, v142, v143
	global_store_dwordx2 v223, v[230:231], s[56:57] offset:288
	v_mul_f32_e32 v140, v13, v13
	v_mul_f32_e32 v141, v15, v15
	v_fmac_f32_e32 v140, v12, v12
	v_fmac_f32_e32 v141, v14, v14
	v_add_f32_e32 v142, v140, v141
	v_mul_f32_e32 v140, v9, v9
	v_mul_f32_e32 v141, v11, v11
	v_fmac_f32_e32 v140, v8, v8
	v_fmac_f32_e32 v141, v10, v10
	v_add_f32_e32 v140, v140, v141
	v_add_f32_e32 v142, v142, v140
	v_mul_f32_e32 v140, v5, v5
	v_mul_f32_e32 v141, v7, v7
	v_fmac_f32_e32 v140, v4, v4
	v_fmac_f32_e32 v141, v6, v6
	v_add_f32_e32 v140, v140, v141
	v_add_f32_e32 v142, v142, v140
	v_mul_f32_e32 v140, v1, v1
	v_mul_f32_e32 v141, v3, v3
	v_fmac_f32_e32 v140, v0, v0
	v_fmac_f32_e32 v141, v2, v2
	v_add_f32_e32 v140, v140, v141
	v_add_f32_e32 v142, v142, v140
	v_mov_b32_e32 v0, v142
	ds_bpermute_b32 v113, v144, v112
	ds_bpermute_b32 v97, v144, v96
	ds_bpermute_b32 v81, v144, v80
	ds_bpermute_b32 v65, v144, v64
	ds_bpermute_b32 v49, v144, v48
	ds_bpermute_b32 v33, v144, v32
	ds_bpermute_b32 v17, v144, v16
	ds_bpermute_b32 v1, v144, v0
	s_waitcnt lgkmcnt(0)
	v_add_f32_e32 v112, v112, v113
	v_add_f32_e32 v96, v96, v97
	v_add_f32_e32 v80, v80, v81
	v_add_f32_e32 v64, v64, v65
	v_add_f32_e32 v48, v48, v49
	v_add_f32_e32 v32, v32, v33
	v_add_f32_e32 v16, v16, v17
	v_add_f32_e32 v0, v0, v1
	ds_bpermute_b32 v113, v145, v112
	ds_bpermute_b32 v97, v145, v96
	ds_bpermute_b32 v81, v145, v80
	ds_bpermute_b32 v65, v145, v64
	ds_bpermute_b32 v49, v145, v48
	ds_bpermute_b32 v33, v145, v32
	ds_bpermute_b32 v17, v145, v16
	ds_bpermute_b32 v1, v145, v0
	s_waitcnt lgkmcnt(0)
	v_add_f32_e32 v112, v112, v113
	v_add_f32_e32 v96, v96, v97
	v_add_f32_e32 v80, v80, v81
	v_add_f32_e32 v64, v64, v65
	v_add_f32_e32 v48, v48, v49
	v_add_f32_e32 v32, v32, v33
	v_add_f32_e32 v16, v16, v17
	v_add_f32_e32 v0, v0, v1
	s_and_saveexec_b64 s[2:3], s[0:1]
	global_atomic_add_f32 v153, v112, s[58:59]
	global_atomic_add_f32 v153, v96, s[58:59] offset:64
	global_atomic_add_f32 v153, v80, s[58:59] offset:128
	global_atomic_add_f32 v153, v64, s[58:59] offset:192
	global_atomic_add_f32 v153, v48, s[58:59] offset:512
	global_atomic_add_f32 v153, v32, s[58:59] offset:576
	global_atomic_add_f32 v153, v16, s[58:59] offset:640
	global_atomic_add_f32 v153, v0, s[58:59] offset:704
	s_or_b64 exec, exec, s[2:3]
	s_andn2_b64 vcc, exec, s[4:5]
	s_mov_b64 s[2:3], -1
	s_cbranch_vccnz .LBB0_725
	s_andn2_b64 vcc, exec, s[8:9]
	s_cbranch_vccnz .LBB0_724
	s_barrier
	s_branch .LBB0_724
